# P1 and P6: last-unit epilogues use write-through (sc1) stores (first units keep write-back stores)
# baseline (speedup 1.0000x reference)
; __device__ __forceinline__ float dot4(f32x4 v) { return (v[0] * v[0] + v[1] * v[1]) + (v[2] * v[2] + v[3] * v[3]); }
; __device__ __forceinline__ u32x2 pack4(f32x4 v) { u32x2 w; w.x = cvt_pk_bf16(v[0], v[1]); w.y = cvt_pk_bf16(v[2], v[3]); return w; }
; __device__ __forceinline__ f32x2 gelu_pk(f32x2 v) {
;     const f32x2 av = __builtin_elementwise_abs(v), d = av * 0.2316418882f + 1.0f;
;     f32x2 t; t.x = __builtin_amdgcn_rcpf(d.x); t.y = __builtin_amdgcn_rcpf(d.y);
;     f32x2 q = t * 0.5307027145f + (-0.7265760135f); q = q * t + 0.7107068705f; q = q * t + (-0.142248368f); q = q * t + 0.127414796f; q = q * t;
;     const f32x2 s = (v * v) * (-0.72134752044f);
;     f32x2 e; e.x = __builtin_amdgcn_exp2f(s.x); e.y = __builtin_amdgcn_exp2f(s.y);
;     const f32x2 m = v * (q * e), r = v - m;
;     f32x2 o; o.x = v.x < 0.f ? m.x : r.x; o.y = v.y < 0.f ? m.y : r.y; return o;
; }
; __device__ __forceinline__ f32x4 gelu4(f32x4 v) { f32x2 a = gelu_pk((f32x2){v[0], v[1]}), b = gelu_pk((f32x2){v[2], v[3]}); return (f32x4){a.x, a.y, b.x, b.y}; }
; template <int EK>
; __device__ __forceinline__ void epi_tile(const f32x4 (&acc)[2][2][4][2], const Unit& u, int wr, int wc, int fr, int fq, const EpiArgs& E, const LAS float* rt) {
;     ...
;             } else if (EK == EK_GELU) {
;                 const float r = rr[ai][m]; float ss = 0.f;
; #pragma unroll
;                 for (int bj = 0; bj < 2; ++bj) { const int col = u.pn * BM + bj * HALF + wc * 32 + fq * 8;
;                     const f32x4 z0 = gelu4(acc[ai][bj][m][0] * r), z1 = gelu4(acc[ai][bj][m][1] * r); ss += dot4(z0) + dot4(z1);
;                     const u32x2 lo = pack4(z0), hi = pack4(z1);
;                     *(u32x4*)(E.ob + (size_t)row * E.ldb + col) = (u32x4){lo.x, lo.y, hi.x, hi.y}; }
.LBB0_932:
	s_cmp_lg_u64 s[6:7], 0
	s_cbranch_scc1 .Lmy_wt_p6
	v_lshl_add_u32 v146, s84, 10, v161
	ds_read2_b32 v[156:157], v146 offset1:16
	ds_read2_b32 v[154:155], v146 offset0:32 offset1:48
	ds_read2_b32 v[152:153], v146 offset0:128 offset1:144
	ds_read2_b32 v[148:149], v146 offset0:160 offset1:176
	v_lshl_add_u32 v150, s22, 8, v1
	s_waitcnt lgkmcnt(0)
	v_pk_mul_f32 v[166:167], v[110:111], v[156:157] op_sel_hi:[1,0]
	v_pk_mul_f32 v[170:171], v[112:113], v[156:157] op_sel_hi:[1,0]
	v_and_b32_e32 v159, 0x7fffffff, v167
	v_and_b32_e32 v158, 0x7fffffff, v166
	v_pk_fma_f32 v[158:159], v[158:159], s[40:41], 1.0 op_sel_hi:[1,0,0]
	v_pk_mul_f32 v[174:175], v[166:167], v[166:167]
	v_rcp_f32_e32 v168, v158
	v_rcp_f32_e32 v169, v159
	v_mov_b64_e32 v[158:159], s[44:45]
	v_pk_mul_f32 v[174:175], v[174:175], s[58:59] op_sel_hi:[1,0]
	v_and_b32_e32 v177, 0x7fffffff, v171
	v_pk_fma_f32 v[172:173], v[168:169], s[42:43], v[158:159] op_sel_hi:[1,0,0]
	v_exp_f32_e32 v174, v174
	v_pk_fma_f32 v[172:173], v[168:169], v[172:173], s[52:53] op_sel_hi:[1,1,0]
	v_exp_f32_e32 v175, v175
	v_pk_fma_f32 v[172:173], v[168:169], v[172:173], s[54:55] op_sel_hi:[1,1,0]
	v_and_b32_e32 v176, 0x7fffffff, v170
	v_pk_fma_f32 v[172:173], v[168:169], v[172:173], s[56:57] op_sel_hi:[1,1,0]
	v_pk_fma_f32 v[176:177], v[176:177], s[40:41], 1.0 op_sel_hi:[1,0,0]
	v_pk_mul_f32 v[168:169], v[168:169], v[172:173]
	v_rcp_f32_e32 v176, v176
	v_rcp_f32_e32 v177, v177
	v_pk_mul_f32 v[168:169], v[174:175], v[168:169]
	v_cmp_gt_f32_e32 vcc, 0, v166
	v_pk_mul_f32 v[174:175], v[166:167], v[168:169]
	v_pk_fma_f32 v[168:169], v[166:167], v[168:169], v[166:167] neg_lo:[1,0,0] neg_hi:[1,0,0]
	v_pk_mul_f32 v[172:173], v[170:171], v[170:171]
	v_cndmask_b32_e32 v165, v168, v174, vcc
	v_cmp_gt_f32_e32 vcc, 0, v167
	v_pk_mul_f32 v[172:173], v[172:173], s[58:59] op_sel_hi:[1,0]
	v_ashrrev_i32_e32 v151, 31, v150
	v_cndmask_b32_e32 v166, v169, v175, vcc
	v_pk_fma_f32 v[168:169], v[176:177], s[42:43], v[158:159] op_sel_hi:[1,0,0]
	v_exp_f32_e32 v172, v172
	v_pk_fma_f32 v[168:169], v[176:177], v[168:169], s[52:53] op_sel_hi:[1,1,0]
	v_exp_f32_e32 v173, v173
	v_pk_fma_f32 v[168:169], v[176:177], v[168:169], s[54:55] op_sel_hi:[1,1,0]
	v_pk_mul_f32 v[174:175], v[106:107], v[156:157] op_sel_hi:[1,0]
	v_pk_fma_f32 v[168:169], v[176:177], v[168:169], s[56:57] op_sel_hi:[1,1,0]
	v_cmp_gt_f32_e32 vcc, 0, v170
	v_pk_mul_f32 v[168:169], v[176:177], v[168:169]
	v_and_b32_e32 v177, 0x7fffffff, v175
	v_and_b32_e32 v176, 0x7fffffff, v174
	v_pk_fma_f32 v[176:177], v[176:177], s[40:41], 1.0 op_sel_hi:[1,0,0]
	v_pk_mul_f32 v[168:169], v[172:173], v[168:169]
	v_rcp_f32_e32 v176, v176
	v_rcp_f32_e32 v177, v177
	v_pk_mul_f32 v[172:173], v[170:171], v[168:169]
	v_pk_fma_f32 v[168:169], v[170:171], v[168:169], v[170:171] neg_lo:[1,0,0] neg_hi:[1,0,0]
	v_pk_mul_f32 v[178:179], v[174:175], v[174:175]
	v_cndmask_b32_e32 v167, v168, v172, vcc
	v_cmp_gt_f32_e32 vcc, 0, v171
	v_pk_fma_f32 v[170:171], v[176:177], s[42:43], v[158:159] op_sel_hi:[1,0,0]
	v_pk_mul_f32 v[178:179], v[178:179], s[58:59] op_sel_hi:[1,0]
	v_cndmask_b32_e32 v168, v169, v173, vcc
	v_pk_mul_f32 v[172:173], v[108:109], v[156:157] op_sel_hi:[1,0]
	v_pk_fma_f32 v[170:171], v[176:177], v[170:171], s[52:53] op_sel_hi:[1,1,0]
	v_exp_f32_e32 v178, v178
	v_exp_f32_e32 v179, v179
	v_and_b32_e32 v181, 0x7fffffff, v173
	v_and_b32_e32 v180, 0x7fffffff, v172
	v_pk_fma_f32 v[170:171], v[176:177], v[170:171], s[54:55] op_sel_hi:[1,1,0]
	v_pk_fma_f32 v[180:181], v[180:181], s[40:41], 1.0 op_sel_hi:[1,0,0]
	v_pk_fma_f32 v[170:171], v[176:177], v[170:171], s[56:57] op_sel_hi:[1,1,0]
	v_rcp_f32_e32 v180, v180
	v_rcp_f32_e32 v181, v181
	v_pk_mul_f32 v[170:171], v[176:177], v[170:171]
	v_cmp_gt_f32_e32 vcc, 0, v174
	v_pk_mul_f32 v[170:171], v[178:179], v[170:171]
	v_pk_mul_f32 v[176:177], v[172:173], v[172:173]
	v_pk_mul_f32 v[178:179], v[174:175], v[170:171]
	v_pk_fma_f32 v[170:171], v[174:175], v[170:171], v[174:175] neg_lo:[1,0,0] neg_hi:[1,0,0]
	v_pk_mul_f32 v[176:177], v[176:177], s[58:59] op_sel_hi:[1,0]
	v_cndmask_b32_e32 v169, v170, v178, vcc
	v_cmp_gt_f32_e32 vcc, 0, v175
	v_pk_fma_f32 v[174:175], v[180:181], s[42:43], v[158:159] op_sel_hi:[1,0,0]
	v_exp_f32_e32 v176, v176
	v_pk_fma_f32 v[174:175], v[180:181], v[174:175], s[52:53] op_sel_hi:[1,1,0]
	v_exp_f32_e32 v177, v177
	v_pk_fma_f32 v[174:175], v[180:181], v[174:175], s[54:55] op_sel_hi:[1,1,0]
	v_lshl_or_b32 v146, s26, 8, v162
	v_pk_fma_f32 v[174:175], v[180:181], v[174:175], s[56:57] op_sel_hi:[1,1,0]
	v_cndmask_b32_e32 v170, v171, v179, vcc
	v_pk_mul_f32 v[174:175], v[180:181], v[174:175]
	v_pk_mul_f32 v[180:181], v[78:79], v[156:157] op_sel_hi:[1,0]
	v_pk_mul_f32 v[174:175], v[176:177], v[174:175]
	v_and_b32_e32 v183, 0x7fffffff, v181
	v_and_b32_e32 v182, 0x7fffffff, v180
	v_pk_fma_f32 v[182:183], v[182:183], s[40:41], 1.0 op_sel_hi:[1,0,0]
	v_pk_mul_f32 v[176:177], v[172:173], v[174:175]
	v_rcp_f32_e32 v182, v182
	v_rcp_f32_e32 v183, v183
	v_pk_fma_f32 v[174:175], v[172:173], v[174:175], v[172:173] neg_lo:[1,0,0] neg_hi:[1,0,0]
	v_cmp_gt_f32_e32 vcc, 0, v172
	v_lshlrev_b64 v[178:179], 12, v[150:151]
	v_lshl_add_u64 v[178:179], s[64:65], 0, v[178:179]
	v_cndmask_b32_e32 v171, v174, v176, vcc
	v_cmp_gt_f32_e32 vcc, 0, v173
	v_ashrrev_i32_e32 v147, 31, v146
	v_cvt_pk_bf16_f32 v174, v165, v166
	v_lshl_add_u64 v[184:185], v[146:147], 1, v[178:179]
	v_cndmask_b32_e32 v172, v175, v177, vcc
	v_cvt_pk_bf16_f32 v175, v167, v168
	v_pk_mul_f32 v[178:179], v[180:181], v[180:181]
	v_cvt_pk_bf16_f32 v176, v169, v170
	v_cvt_pk_bf16_f32 v177, v171, v172
	global_store_dwordx4 v[184:185], v[174:177], off
; __device__ __forceinline__ float dot4(f32x4 v) { return (v[0] * v[0] + v[1] * v[1]) + (v[2] * v[2] + v[3] * v[3]); }
; __device__ __forceinline__ u32x2 pack4(f32x4 v) { u32x2 w; w.x = cvt_pk_bf16(v[0], v[1]); w.y = cvt_pk_bf16(v[2], v[3]); return w; }
; __device__ __forceinline__ f32x4 gelu4(f32x4 v) { f32x2 a = gelu_pk((f32x2){v[0], v[1]}), b = gelu_pk((f32x2){v[2], v[3]}); return (f32x4){a.x, a.y, b.x, b.y}; }
; __device__ __forceinline__ float wave_sum(float s) { s += __shfl_xor(s, 1); s += __shfl_xor(s, 2); s += __shfl_xor(s, 4); s += __shfl_xor(s, 8); s += __shfl_xor(s, 16); s += __shfl_xor(s, 32); return s; }
; __device__ __forceinline__ float quad_sum(float s) { s += __shfl_xor(s, 16); s += __shfl_xor(s, 32); return s; }
; template <int EK>
; __device__ __forceinline__ void epi_tile(const f32x4 (&acc)[2][2][4][2], const Unit& u, int wr, int wc, int fr, int fq, const EpiArgs& E, const LAS float* rt) {
;     ...
;             } else if (EK == EK_GELU) {
;                 const float r = rr[ai][m]; float ss = 0.f;
; #pragma unroll
;                 for (int bj = 0; bj < 2; ++bj) { const int col = u.pn * BM + bj * HALF + wc * 32 + fq * 8;
;                     const f32x4 z0 = gelu4(acc[ai][bj][m][0] * r), z1 = gelu4(acc[ai][bj][m][1] * r); ss += dot4(z0) + dot4(z1);
;                     const u32x2 lo = pack4(z0), hi = pack4(z1);
;                     *(u32x4*)(E.ob + (size_t)row * E.ldb + col) = (u32x4){lo.x, lo.y, hi.x, hi.y}; }
;                 if (u.pn >= 4) { ss = quad_sum(ss); if (fq == 0) E.stOut[(size_t)row * 16 + (u.pn - 4) * 4 + wc] = ss; }
	v_pk_mul_f32 v[178:179], v[178:179], s[58:59] op_sel_hi:[1,0]
	v_cmp_gt_f32_e32 vcc, 0, v180
	v_pk_fma_f32 v[174:175], v[182:183], s[42:43], v[158:159] op_sel_hi:[1,0,0]
	v_pk_mul_f32 v[176:177], v[80:81], v[156:157] op_sel_hi:[1,0]
	v_pk_fma_f32 v[174:175], v[182:183], v[174:175], s[52:53] op_sel_hi:[1,1,0]
	v_exp_f32_e32 v178, v178
	v_exp_f32_e32 v179, v179
	v_pk_fma_f32 v[174:175], v[182:183], v[174:175], s[54:55] op_sel_hi:[1,1,0]
	v_and_b32_e32 v187, 0x7fffffff, v177
	v_and_b32_e32 v186, 0x7fffffff, v176
	v_pk_fma_f32 v[174:175], v[182:183], v[174:175], s[56:57] op_sel_hi:[1,1,0]
	v_pk_fma_f32 v[186:187], v[186:187], s[40:41], 1.0 op_sel_hi:[1,0,0]
	v_pk_mul_f32 v[174:175], v[182:183], v[174:175]
	v_rcp_f32_e32 v186, v186
	v_rcp_f32_e32 v187, v187
	v_pk_mul_f32 v[174:175], v[178:179], v[174:175]
	v_pk_mul_f32 v[182:183], v[176:177], v[176:177]
	v_pk_mul_f32 v[178:179], v[180:181], v[174:175]
	v_pk_fma_f32 v[174:175], v[180:181], v[174:175], v[180:181] neg_lo:[1,0,0] neg_hi:[1,0,0]
	s_cmp_gt_i32 s26, 3
	v_cndmask_b32_e32 v173, v174, v178, vcc
	v_cmp_gt_f32_e32 vcc, 0, v181
	v_pk_mul_f32 v[180:181], v[182:183], s[58:59] op_sel_hi:[1,0]
	v_pk_mul_f32 v[182:183], v[74:75], v[156:157] op_sel_hi:[1,0]
	v_cndmask_b32_e32 v174, v175, v179, vcc
	v_pk_fma_f32 v[178:179], v[186:187], s[42:43], v[158:159] op_sel_hi:[1,0,0]
	v_exp_f32_e32 v180, v180
	v_pk_fma_f32 v[178:179], v[186:187], v[178:179], s[52:53] op_sel_hi:[1,1,0]
	v_exp_f32_e32 v181, v181
	v_pk_fma_f32 v[178:179], v[186:187], v[178:179], s[54:55] op_sel_hi:[1,1,0]
	v_cmp_gt_f32_e32 vcc, 0, v176
	v_pk_fma_f32 v[178:179], v[186:187], v[178:179], s[56:57] op_sel_hi:[1,1,0]
	v_pk_mul_f32 v[188:189], v[182:183], v[182:183]
	v_pk_mul_f32 v[178:179], v[186:187], v[178:179]
	v_and_b32_e32 v187, 0x7fffffff, v183
	v_and_b32_e32 v186, 0x7fffffff, v182
	v_pk_fma_f32 v[186:187], v[186:187], s[40:41], 1.0 op_sel_hi:[1,0,0]
	v_pk_mul_f32 v[178:179], v[180:181], v[178:179]
	v_rcp_f32_e32 v186, v186
	v_rcp_f32_e32 v187, v187
	v_pk_mul_f32 v[180:181], v[176:177], v[178:179]
	v_pk_fma_f32 v[178:179], v[176:177], v[178:179], v[176:177] neg_lo:[1,0,0] neg_hi:[1,0,0]
	v_pk_mul_f32 v[188:189], v[188:189], s[58:59] op_sel_hi:[1,0]
	v_cndmask_b32_e32 v175, v178, v180, vcc
	v_cmp_gt_f32_e32 vcc, 0, v177
	v_exp_f32_e32 v188, v188
	v_exp_f32_e32 v189, v189
	v_cndmask_b32_e32 v176, v179, v181, vcc
	v_pk_fma_f32 v[180:181], v[186:187], s[42:43], v[158:159] op_sel_hi:[1,0,0]
	v_pk_mul_f32 v[178:179], v[76:77], v[156:157] op_sel_hi:[1,0]
	v_pk_fma_f32 v[180:181], v[186:187], v[180:181], s[52:53] op_sel_hi:[1,1,0]
	v_and_b32_e32 v191, 0x7fffffff, v179
	v_pk_fma_f32 v[180:181], v[186:187], v[180:181], s[54:55] op_sel_hi:[1,1,0]
	v_and_b32_e32 v190, 0x7fffffff, v178
	v_pk_fma_f32 v[180:181], v[186:187], v[180:181], s[56:57] op_sel_hi:[1,1,0]
	v_pk_fma_f32 v[190:191], v[190:191], s[40:41], 1.0 op_sel_hi:[1,0,0]
	v_pk_mul_f32 v[180:181], v[186:187], v[180:181]
	v_rcp_f32_e32 v190, v190
	v_rcp_f32_e32 v191, v191
	v_pk_mul_f32 v[180:181], v[188:189], v[180:181]
	v_cmp_gt_f32_e32 vcc, 0, v182
	v_pk_mul_f32 v[188:189], v[182:183], v[180:181]
	v_pk_fma_f32 v[180:181], v[182:183], v[180:181], v[182:183] neg_lo:[1,0,0] neg_hi:[1,0,0]
	v_pk_mul_f32 v[186:187], v[178:179], v[178:179]
	v_cndmask_b32_e32 v156, v180, v188, vcc
	v_cmp_gt_f32_e32 vcc, 0, v183
	v_pk_fma_f32 v[158:159], v[190:191], s[42:43], v[158:159] op_sel_hi:[1,0,0]
	s_cselect_b64 s[78:79], -1, 0
	v_cndmask_b32_e32 v177, v181, v189, vcc
	v_pk_mul_f32 v[180:181], v[186:187], s[58:59] op_sel_hi:[1,0]
	v_pk_fma_f32 v[158:159], v[190:191], v[158:159], s[52:53] op_sel_hi:[1,1,0]
	v_exp_f32_e32 v180, v180
	v_exp_f32_e32 v181, v181
	v_pk_fma_f32 v[158:159], v[190:191], v[158:159], s[54:55] op_sel_hi:[1,1,0]
	s_lshl_b32 s10, s26, 2
	v_pk_fma_f32 v[158:159], v[190:191], v[158:159], s[56:57] op_sel_hi:[1,1,0]
	s_add_i32 s76, s10, -16
	v_pk_mul_f32 v[158:159], v[190:191], v[158:159]
	v_cmp_gt_f32_e32 vcc, 0, v178
	v_pk_mul_f32 v[158:159], v[180:181], v[158:159]
	s_ashr_i32 s77, s76, 31
	v_pk_mul_f32 v[180:181], v[178:179], v[158:159]
	v_pk_fma_f32 v[158:159], v[178:179], v[158:159], v[178:179] neg_lo:[1,0,0] neg_hi:[1,0,0]
	s_cmp_lt_i32 s26, 4
	v_cndmask_b32_e32 v158, v158, v180, vcc
	v_cmp_gt_f32_e32 vcc, 0, v179
	v_cvt_pk_bf16_f32 v178, v173, v174
	v_cvt_pk_bf16_f32 v179, v175, v176
	v_cvt_pk_bf16_f32 v180, v156, v177
	s_nop 1
	v_cndmask_b32_e32 v159, v159, v181, vcc
	v_cvt_pk_bf16_f32 v181, v158, v159
	global_store_dwordx4 v[184:185], v[178:181], off offset:256
	s_cbranch_scc1 .LBB0_936
	v_mul_f32_e32 v166, v166, v166
	v_fmac_f32_e32 v166, v165, v165
	v_mul_f32_e32 v165, v168, v168
	v_fmac_f32_e32 v165, v167, v167
	v_add_f32_e32 v165, v166, v165
	v_mul_f32_e32 v166, v170, v170
	v_mul_f32_e32 v167, v172, v172
	v_fmac_f32_e32 v166, v169, v169
	v_fmac_f32_e32 v167, v171, v171
	v_add_f32_e32 v166, v166, v167
	v_add_f32_e32 v165, v165, v166
	v_mul_f32_e32 v166, v174, v174
	v_mul_f32_e32 v167, v176, v176
	v_fmac_f32_e32 v166, v173, v173
	v_fmac_f32_e32 v167, v175, v175
	v_add_f32_e32 v166, v166, v167
	v_mul_f32_e32 v167, v177, v177
	v_fmac_f32_e32 v167, v156, v156
	v_mul_f32_e32 v156, v159, v159
	v_and_b32_e32 v159, 64, v164
	v_fmac_f32_e32 v156, v158, v158
	v_xor_b32_e32 v158, 16, v164
	v_add_u32_e32 v159, 64, v159
	v_add_f32_e32 v156, v167, v156
	v_cmp_lt_i32_e32 vcc, v158, v159
	v_add_f32_e32 v156, v166, v156
	v_add_f32_e32 v156, v165, v156
	v_cndmask_b32_e32 v158, v164, v158, vcc
	v_lshlrev_b32_e32 v158, 2, v158
	ds_bpermute_b32 v158, v158, v156
	s_waitcnt lgkmcnt(0)
	v_add_f32_e32 v156, v156, v158
	v_xor_b32_e32 v158, 32, v164
	v_cmp_lt_i32_e32 vcc, v158, v159
	s_nop 1
	v_cndmask_b32_e32 v158, v164, v158, vcc
	v_lshlrev_b32_e32 v158, 2, v158
	ds_bpermute_b32 v158, v158, v156
	s_and_saveexec_b64 s[10:11], s[4:5]
	s_cbranch_execz .LBB0_935
	v_lshlrev_b64 v[166:167], 6, v[150:151]
	v_lshl_add_u64 v[166:167], s[18:19], 0, v[166:167]
	v_lshl_add_u64 v[166:167], s[76:77], 2, v[166:167]
	s_lshl_b32 s14, s59, 2
	v_lshl_add_u64 v[166:167], v[166:167], 0, s[14:15]
	s_waitcnt lgkmcnt(0)
	v_add_f32_e32 v151, v156, v158
	global_store_dword v[166:167], v151, off

; __device__ __forceinline__ float quad_sum(float s) { s += __shfl_xor(s, 16); s += __shfl_xor(s, 32); return s; }
; template <int EK>
; __device__ __forceinline__ void epi_tile(const f32x4 (&acc)[2][2][4][2], const Unit& u, int wr, int wc, int fr, int fq, const EpiArgs& E, const LAS float* rt) {
;     ...
;                 if (u.pn >= 4) { ss = quad_sum(ss); if (fq == 0) E.stOut[(size_t)row * 16 + (u.pn - 4) * 4 + wc] = ss; }
.LBB0_963:
	s_or_b64 exec, exec, s[10:11]
	s_branch .Lmy_wtj_p6

; #define PG8_BAR __builtin_amdgcn_s_barrier()
; template <int EK, int SK = -1>
; __device__ __forceinline__ void gemm_phase(LAS unsigned char* lds, const bf16_t* A, const bf16_t* Bt, int nM, int N, int K, const EpiArgs& E) {
;     ...
;         if (EK != EK_FINAL) epi_tile<EK>(acc, cur, wr, wc, fr, fq, E, rtab + ui * 256);
;         if (!has_next) break;
; #pragma unroll
;         for (int a = 0; a < 2; ++a)
; #pragma unroll
;             for (int b = 0; b < 2; ++b)
; #pragma unroll
;                 for (int m = 0; m < 4; ++m)
; #pragma unroll
;                     for (int n = 0; n < 2; ++n) acc[a][b][m][n] = (f32x4){0.f, 0.f, 0.f, 0.f};
;         cur = nxt; cA = nA; cB = nB; ++ui;
;         if (wr == 1) PG8_BAR;
.Lmy_wtj_p6:
.LBB0_964:
	s_add_u32 s10, s86, 0xffffff00
	s_addc_u32 s11, s87, -1
	s_andn2_b64 vcc, exec, s[8:9]
	s_cbranch_vccnz .LBB0_967
	s_andn2_b64 vcc, exec, s[12:13]
	s_cbranch_vccnz .LBB0_921
	s_barrier
	s_branch .LBB0_921
